# store-drain waits removed from loop tops (LN2 stage, P2 conv, P2 local, P4: wait only for loads, full wait hoisted before loop entry); P2 local wave-0 scans via DPP
# speedup vs baseline: 1.0158x; 1.0158x over previous
.LBB0_247:
	s_or_b64 exec, exec, s[0:1]
	v_lshlrev_b32_e32 v41, 1, v101
	v_and_b32_e32 v80, 0x7f0, v41
	v_ashrrev_i32_e32 v41, 31, v40
	v_lshlrev_b64 v[42:43], 12, v[40:41]
	v_lshl_add_u64 v[82:83], s[80:81], 0, v[42:43]
	v_mov_b64_e32 v[42:43], s[80:81]
	v_or_b32_e32 v102, 24, v40
	v_add_u32_e32 v103, -8, v40
	v_mad_i64_i32 v[84:85], s[0:1], v40, s23, v[42:43]
	s_mov_b64 s[14:15], 0
	s_waitcnt vmcnt(0)
.LBB0_248:
	v_lshl_add_u64 v[86:87], v[84:85], 0, v[80:81]
	v_add_co_u32_e32 v40, vcc, 0x8000000, v86
	v_fma_f32 v104, v24, v50, v28
	v_addc_co_u32_e32 v41, vcc, 0, v87, vcc
	v_fma_f32 v105, v25, v51, v29
	v_fma_f32 v109, v24, v32, v28
	v_fmac_f32_e32 v104, v0, v32
	v_add_co_u32_e32 v32, vcc, 0x8001000, v86
	v_fma_f32 v106, v26, v48, v30
	v_fma_f32 v111, v25, v33, v29
	v_fmac_f32_e32 v105, v1, v33
	v_addc_co_u32_e32 v33, vcc, 0, v87, vcc
	v_fma_f32 v107, v27, v49, v31
	v_fma_f32 v113, v26, v34, v30
	v_fmac_f32_e32 v106, v2, v34
	v_add_co_u32_e32 v34, vcc, 0x8003000, v86
	v_fma_f32 v108, v16, v46, v20
	v_fma_f32 v115, v27, v35, v31
	v_fmac_f32_e32 v107, v3, v35
	v_addc_co_u32_e32 v35, vcc, 0, v87, vcc
	v_fma_f32 v110, v17, v47, v21
	v_fma_f32 v116, v16, v36, v20
	v_fmac_f32_e32 v108, v4, v36
	v_add_co_u32_e32 v36, vcc, 0x8004000, v86
	v_fma_f32 v117, v17, v37, v21
	v_fmac_f32_e32 v110, v5, v37
	v_addc_co_u32_e32 v37, vcc, 0, v87, vcc
	global_load_dwordx4 v[120:123], v[40:41], off
	global_load_dwordx4 v[124:127], v[40:41], off offset:2048
	global_load_dwordx4 v[130:133], v[32:33], off
	global_load_dwordx4 v[134:137], v[34:35], off offset:2048
	v_add_co_u32_e32 v32, vcc, 0x8007000, v86
	global_load_dwordx4 v[138:141], v[36:37], off
	global_load_dwordx4 v[142:145], v[36:37], off offset:2048
	v_addc_co_u32_e32 v33, vcc, 0, v87, vcc
	v_add_co_u32_e32 v34, vcc, 0x8008000, v86
	global_load_dwordx4 v[146:149], v[32:33], off
	global_load_dwordx4 v[150:153], v[32:33], off offset:2048
	v_addc_co_u32_e32 v35, vcc, 0, v87, vcc
	v_add_co_u32_e32 v32, vcc, 0x800a000, v86
	v_fma_f32 v112, v18, v44, v22
	s_nop 0
	v_addc_co_u32_e32 v33, vcc, 0, v87, vcc
	v_add_co_u32_e32 v36, vcc, 0x800b000, v86
	global_load_dwordx4 v[154:157], v[34:35], off
	global_load_dwordx4 v[158:161], v[32:33], off offset:2048
	v_addc_co_u32_e32 v37, vcc, 0, v87, vcc
	v_add_co_u32_e32 v32, vcc, 0x800e000, v86
	global_load_dwordx4 v[162:165], v[36:37], off
	global_load_dwordx4 v[166:169], v[36:37], off offset:2048
	v_addc_co_u32_e32 v33, vcc, 0, v87, vcc
	v_add_co_u32_e32 v34, vcc, 0x800f000, v86
	global_load_dwordx4 v[76:79], v[32:33], off
	global_load_dwordx4 v[72:75], v[32:33], off offset:2048
	v_addc_co_u32_e32 v35, vcc, 0, v87, vcc
	v_add_co_u32_e32 v32, vcc, 0x8011000, v86
	v_fma_f32 v114, v19, v45, v23
	s_nop 0
	v_addc_co_u32_e32 v33, vcc, 0, v87, vcc
	v_add_co_u32_e32 v36, vcc, 0x8012000, v86
	global_load_dwordx4 v[68:71], v[34:35], off
	global_load_dwordx4 v[64:67], v[32:33], off offset:2048
	v_addc_co_u32_e32 v37, vcc, 0, v87, vcc
	v_add_co_u32_e32 v32, vcc, 0x8015000, v86
	global_load_dwordx4 v[60:63], v[36:37], off
	global_load_dwordx4 v[56:59], v[36:37], off offset:2048
	v_addc_co_u32_e32 v33, vcc, 0, v87, vcc
	v_add_co_u32_e32 v34, vcc, 0x8016000, v86
	global_load_dwordx4 v[52:55], v[32:33], off
	global_load_dwordx4 v[48:51], v[32:33], off offset:2048
	v_addc_co_u32_e32 v35, vcc, 0, v87, vcc
	v_add_co_u32_e32 v32, vcc, 0x8018000, v86
	v_fma_f32 v118, v18, v38, v22
	s_nop 0
	v_addc_co_u32_e32 v33, vcc, 0, v87, vcc
	v_add_co_u32_e32 v170, vcc, 0x8019000, v86
	global_load_dwordx4 v[44:47], v[34:35], off
	global_load_dwordx4 v[40:43], v[32:33], off offset:2048
	v_addc_co_u32_e32 v171, vcc, 0, v87, vcc
	v_fma_f32 v119, v19, v39, v23
	v_fmac_f32_e32 v112, v6, v38
	v_fmac_f32_e32 v114, v7, v39
	global_load_dwordx4 v[36:39], v[170:171], off
	global_load_dwordx4 v[32:35], v[170:171], off offset:2048
	v_lshl_add_u64 v[88:89], v[82:83], 0, v[80:81]
	v_add_co_u32_e64 v96, s[0:1], s24, v88
	v_add_co_u32_e32 v86, vcc, 0x24007000, v88
	s_nop 0
	v_addc_co_u32_e64 v97, s[0:1], 0, v89, s[0:1]
	v_add_co_u32_e64 v94, s[0:1], s25, v88
	v_addc_co_u32_e32 v87, vcc, 0, v89, vcc
	s_nop 0
	v_addc_co_u32_e64 v95, s[0:1], 0, v89, s[0:1]
	v_add_co_u32_e64 v92, s[0:1], s26, v88
	s_waitcnt vmcnt(0)
	v_lshlrev_b32_e32 v171, 16, v124
	v_addc_co_u32_e64 v93, s[0:1], 0, v89, s[0:1]
	v_and_b32_e32 v124, 0xffff0000, v124
	v_lshlrev_b32_e32 v172, 16, v125
	v_and_b32_e32 v125, 0xffff0000, v125
	v_lshlrev_b32_e32 v173, 16, v126
	v_and_b32_e32 v126, 0xffff0000, v126
	v_lshlrev_b32_e32 v174, 16, v127
	v_and_b32_e32 v127, 0xffff0000, v127
	v_lshlrev_b32_e32 v175, 16, v130
	v_and_b32_e32 v130, 0xffff0000, v130
	v_lshlrev_b32_e32 v176, 16, v131
	v_and_b32_e32 v131, 0xffff0000, v131
	v_lshlrev_b32_e32 v177, 16, v132
	v_and_b32_e32 v132, 0xffff0000, v132
	v_lshlrev_b32_e32 v178, 16, v133
	v_and_b32_e32 v133, 0xffff0000, v133
	v_add_co_u32_e64 v90, s[0:1], s27, v88
	v_mul_f32_e32 v171, v171, v175
	v_mul_f32_e32 v124, v124, v130
	v_mul_f32_e32 v130, v172, v176
	v_mul_f32_e32 v125, v125, v131
	v_mul_f32_e32 v131, v173, v177
	v_mul_f32_e32 v126, v126, v132
	v_mul_f32_e32 v132, v174, v178
	v_mul_f32_e32 v127, v127, v133
	v_addc_co_u32_e64 v91, s[0:1], 0, v89, s[0:1]
	v_lshlrev_b32_e32 v88, 16, v120
	v_and_b32_e32 v89, 0xffff0000, v120
	v_lshlrev_b32_e32 v120, 16, v121
	v_and_b32_e32 v121, 0xffff0000, v121
	v_lshlrev_b32_e32 v129, 16, v122
	v_and_b32_e32 v122, 0xffff0000, v122
	v_lshlrev_b32_e32 v170, 16, v123
	v_and_b32_e32 v123, 0xffff0000, v123
	v_fmac_f32_e32 v104, v8, v171
	v_fmac_f32_e32 v105, v9, v124
	v_fmac_f32_e32 v106, v10, v130
	v_fmac_f32_e32 v107, v11, v125
	v_fmac_f32_e32 v108, v12, v131
	v_fmac_f32_e32 v110, v13, v126
	v_fmac_f32_e32 v112, v14, v132
	v_fmac_f32_e32 v114, v15, v127
	v_lshlrev_b32_e32 v175, 16, v138
	v_and_b32_e32 v138, 0xffff0000, v138
	v_lshlrev_b32_e32 v176, 16, v139
	v_and_b32_e32 v139, 0xffff0000, v139
	v_lshlrev_b32_e32 v177, 16, v140
	v_and_b32_e32 v140, 0xffff0000, v140
	v_lshlrev_b32_e32 v178, 16, v141
	v_and_b32_e32 v141, 0xffff0000, v141
	v_lshlrev_b32_e32 v179, 16, v142
	v_and_b32_e32 v142, 0xffff0000, v142
	v_lshlrev_b32_e32 v180, 16, v143
	v_and_b32_e32 v143, 0xffff0000, v143
	v_lshlrev_b32_e32 v181, 16, v144
	v_and_b32_e32 v144, 0xffff0000, v144
	v_lshlrev_b32_e32 v182, 16, v145
	v_and_b32_e32 v145, 0xffff0000, v145
	v_fmac_f32_e32 v109, v0, v171
	v_fmac_f32_e32 v111, v1, v124
	v_fmac_f32_e32 v113, v2, v130
	v_fmac_f32_e32 v115, v3, v125
	v_fmac_f32_e32 v116, v4, v131
	v_fmac_f32_e32 v117, v5, v126
	v_fmac_f32_e32 v118, v6, v132
	v_fmac_f32_e32 v119, v7, v127
	v_mul_f32_e32 v88, v104, v88
	v_mul_f32_e32 v89, v105, v89
	v_mul_f32_e32 v105, v106, v120
	v_mul_f32_e32 v106, v107, v121
	v_mul_f32_e32 v107, v108, v129
	v_mul_f32_e32 v108, v110, v122
	v_mul_f32_e32 v110, v112, v170
	v_mul_f32_e32 v112, v114, v123
	v_mul_f32_e32 v114, v175, v179
	v_mul_f32_e32 v120, v138, v142
	v_mul_f32_e32 v121, v176, v180
	v_mul_f32_e32 v122, v139, v143
	v_mul_f32_e32 v123, v177, v181
	v_mul_f32_e32 v129, v140, v144
	v_mul_f32_e32 v138, v178, v182
	v_mul_f32_e32 v139, v141, v145
	v_lshlrev_b32_e32 v133, 16, v134
	v_and_b32_e32 v134, 0xffff0000, v134
	v_lshlrev_b32_e32 v172, 16, v135
	v_and_b32_e32 v135, 0xffff0000, v135
	v_lshlrev_b32_e32 v173, 16, v136
	v_and_b32_e32 v136, 0xffff0000, v136
	v_lshlrev_b32_e32 v174, 16, v137
	v_and_b32_e32 v137, 0xffff0000, v137
	v_fma_f32 v171, v24, v171, v28
	v_fma_f32 v124, v25, v124, v29
	v_fma_f32 v130, v26, v130, v30
	v_fma_f32 v125, v27, v125, v31
	v_fma_f32 v131, v16, v131, v20
	v_fma_f32 v126, v17, v126, v21
	v_fma_f32 v127, v19, v127, v23
	v_lshlrev_b32_e32 v140, 16, v146
	v_and_b32_e32 v141, 0xffff0000, v146
	v_lshlrev_b32_e32 v142, 16, v147
	v_and_b32_e32 v143, 0xffff0000, v147
	v_lshlrev_b32_e32 v144, 16, v148
	v_and_b32_e32 v145, 0xffff0000, v148
	v_lshlrev_b32_e32 v146, 16, v149
	v_and_b32_e32 v147, 0xffff0000, v149
	v_lshlrev_b32_e32 v148, 16, v150
	v_and_b32_e32 v149, 0xffff0000, v150
	v_lshlrev_b32_e32 v150, 16, v151
	v_and_b32_e32 v151, 0xffff0000, v151
	v_lshlrev_b32_e32 v170, 16, v152
	v_and_b32_e32 v152, 0xffff0000, v152
	v_lshlrev_b32_e32 v175, 16, v153
	v_and_b32_e32 v153, 0xffff0000, v153
	v_cvt_pk_bf16_f32 v104, v88, v89
	v_cvt_pk_bf16_f32 v105, v105, v106
	v_cvt_pk_bf16_f32 v106, v107, v108
	v_cvt_pk_bf16_f32 v107, v110, v112
	v_fmac_f32_e32 v109, v8, v114
	v_fmac_f32_e32 v111, v9, v120
	v_fmac_f32_e32 v113, v10, v121
	v_fmac_f32_e32 v115, v11, v122
	v_fmac_f32_e32 v116, v12, v123
	v_fmac_f32_e32 v117, v13, v129
	v_fmac_f32_e32 v118, v14, v138
	v_fmac_f32_e32 v119, v15, v139
	v_lshlrev_b32_e32 v88, 16, v154
	v_and_b32_e32 v89, 0xffff0000, v154
	v_lshlrev_b32_e32 v108, 16, v155
	v_and_b32_e32 v110, 0xffff0000, v155
	v_lshlrev_b32_e32 v112, 16, v156
	v_and_b32_e32 v154, 0xffff0000, v156
	v_and_b32_e32 v156, 0xffff0000, v157
	v_fma_f32 v132, v18, v132, v22
	v_lshlrev_b32_e32 v155, 16, v157
	v_fmac_f32_e32 v171, v0, v114
	v_fmac_f32_e32 v124, v1, v120
	v_fmac_f32_e32 v130, v2, v121
	v_fmac_f32_e32 v125, v3, v122
	v_fmac_f32_e32 v131, v4, v123
	v_fmac_f32_e32 v126, v5, v129
	v_fmac_f32_e32 v127, v7, v139
	global_store_dwordx4 v[96:97], v[104:107], off offset:-4096
	v_mul_f32_e32 v88, v148, v88
	v_mul_f32_e32 v89, v149, v89
	v_mul_f32_e32 v104, v109, v133
	v_mul_f32_e32 v105, v111, v134
	v_mul_f32_e32 v106, v113, v172
	v_mul_f32_e32 v107, v115, v135
	v_mul_f32_e32 v109, v116, v173
	v_mul_f32_e32 v111, v117, v136
	v_mul_f32_e32 v113, v118, v174
	v_mul_f32_e32 v115, v119, v137
	v_mul_f32_e32 v108, v150, v108
	v_mul_f32_e32 v110, v151, v110
	v_mul_f32_e32 v112, v170, v112
	v_mul_f32_e32 v116, v152, v154
	v_mul_f32_e32 v118, v153, v156
	v_fmac_f32_e32 v132, v6, v138
	v_fma_f32 v114, v24, v114, v28
	v_fma_f32 v120, v25, v120, v29
	v_fma_f32 v121, v26, v121, v30
	v_fma_f32 v122, v27, v122, v31
	v_fma_f32 v123, v16, v123, v20
	v_fma_f32 v129, v17, v129, v21
	v_fma_f32 v138, v18, v138, v22
	v_fma_f32 v139, v19, v139, v23
	v_mul_f32_e32 v117, v175, v155
	v_lshlrev_b32_e32 v119, 16, v158
	v_and_b32_e32 v133, 0xffff0000, v158
	v_lshlrev_b32_e32 v134, 16, v159
	v_and_b32_e32 v135, 0xffff0000, v159
	v_lshlrev_b32_e32 v136, 16, v160
	v_and_b32_e32 v137, 0xffff0000, v160
	v_lshlrev_b32_e32 v148, 16, v161
	v_and_b32_e32 v149, 0xffff0000, v161
	v_cvt_pk_bf16_f32 v104, v104, v105
	v_cvt_pk_bf16_f32 v105, v106, v107
	v_cvt_pk_bf16_f32 v106, v109, v111
	v_cvt_pk_bf16_f32 v107, v113, v115
	v_fmac_f32_e32 v171, v8, v88
	v_fmac_f32_e32 v124, v9, v89
	v_fmac_f32_e32 v130, v10, v108
	v_fmac_f32_e32 v125, v11, v110
	v_fmac_f32_e32 v131, v12, v112
	v_fmac_f32_e32 v126, v13, v116
	v_fmac_f32_e32 v127, v15, v118
	v_lshlrev_b32_e32 v109, 16, v162
	v_and_b32_e32 v111, 0xffff0000, v162
	v_lshlrev_b32_e32 v113, 16, v163
	v_and_b32_e32 v115, 0xffff0000, v163
	v_lshlrev_b32_e32 v150, 16, v164
	v_and_b32_e32 v151, 0xffff0000, v164
	v_lshlrev_b32_e32 v152, 16, v165
	v_and_b32_e32 v153, 0xffff0000, v165
	v_lshlrev_b32_e32 v154, 16, v166
	v_and_b32_e32 v155, 0xffff0000, v166
	v_lshlrev_b32_e32 v156, 16, v167
	v_and_b32_e32 v157, 0xffff0000, v167
	v_lshlrev_b32_e32 v158, 16, v168
	v_and_b32_e32 v159, 0xffff0000, v168
	v_lshlrev_b32_e32 v160, 16, v169
	v_and_b32_e32 v161, 0xffff0000, v169
	v_fmac_f32_e32 v132, v14, v117
	v_fmac_f32_e32 v114, v0, v88
	v_fmac_f32_e32 v120, v1, v89
	v_fmac_f32_e32 v121, v2, v108
	v_fmac_f32_e32 v122, v3, v110
	v_fmac_f32_e32 v123, v4, v112
	v_fmac_f32_e32 v129, v5, v116
	v_fmac_f32_e32 v138, v6, v117
	v_fmac_f32_e32 v139, v7, v118
	global_store_dwordx4 v[96:97], v[104:107], off
	v_mul_f32_e32 v96, v171, v140
	v_mul_f32_e32 v97, v124, v141
	v_mul_f32_e32 v104, v130, v142
	v_mul_f32_e32 v105, v125, v143
	v_mul_f32_e32 v106, v131, v144
	v_mul_f32_e32 v107, v126, v145
	v_mul_f32_e32 v125, v127, v147
	v_mul_f32_e32 v109, v109, v154
	v_mul_f32_e32 v111, v111, v155
	v_mul_f32_e32 v113, v113, v156
	v_mul_f32_e32 v115, v115, v157
	v_mul_f32_e32 v126, v150, v158
	v_mul_f32_e32 v127, v151, v159
	v_mul_f32_e32 v130, v152, v160
	v_mul_f32_e32 v131, v153, v161
	v_fma_f32 v88, v24, v88, v28
	v_fma_f32 v89, v25, v89, v29
	v_fma_f32 v108, v26, v108, v30
	v_fma_f32 v110, v27, v110, v31
	v_fma_f32 v112, v16, v112, v20
	v_fma_f32 v116, v17, v116, v21
	v_fma_f32 v117, v18, v117, v22
	v_fma_f32 v118, v19, v118, v23
	v_mul_f32_e32 v124, v132, v146
	v_lshlrev_b32_e32 v143, 16, v72
	v_and_b32_e32 v144, 0xffff0000, v72
	v_lshlrev_b32_e32 v145, 16, v73
	v_and_b32_e32 v146, 0xffff0000, v73
	v_lshlrev_b32_e32 v147, 16, v74
	v_and_b32_e32 v150, 0xffff0000, v74
	v_lshlrev_b32_e32 v151, 16, v75
	v_and_b32_e32 v152, 0xffff0000, v75
	v_cvt_pk_bf16_f32 v72, v96, v97
	v_cvt_pk_bf16_f32 v73, v104, v105
	v_cvt_pk_bf16_f32 v74, v106, v107
	v_cvt_pk_bf16_f32 v75, v124, v125
	v_fmac_f32_e32 v114, v8, v109
	v_fmac_f32_e32 v120, v9, v111
	v_fmac_f32_e32 v121, v10, v113
	v_fmac_f32_e32 v122, v11, v115
	v_fmac_f32_e32 v123, v12, v126
	v_fmac_f32_e32 v129, v13, v127
	v_fmac_f32_e32 v138, v14, v130
	v_fmac_f32_e32 v139, v15, v131
	v_lshlrev_b32_e32 v96, 16, v68
	v_and_b32_e32 v68, 0xffff0000, v68
	v_lshlrev_b32_e32 v97, 16, v69
	v_and_b32_e32 v69, 0xffff0000, v69
	v_lshlrev_b32_e32 v104, 16, v70
	v_and_b32_e32 v70, 0xffff0000, v70
	v_lshlrev_b32_e32 v105, 16, v71
	v_and_b32_e32 v71, 0xffff0000, v71
	v_fmac_f32_e32 v88, v0, v109
	v_fmac_f32_e32 v89, v1, v111
	v_fmac_f32_e32 v108, v2, v113
	v_fmac_f32_e32 v110, v3, v115
	v_fmac_f32_e32 v112, v4, v126
	v_fmac_f32_e32 v116, v5, v127
	v_fmac_f32_e32 v117, v6, v130
	v_fmac_f32_e32 v118, v7, v131
	global_store_dwordx4 v[94:95], v[72:75], off offset:-4096
	v_mul_f32_e32 v96, v143, v96
	v_mul_f32_e32 v68, v144, v68
	v_mul_f32_e32 v72, v114, v119
	v_mul_f32_e32 v73, v120, v133
	v_mul_f32_e32 v74, v121, v134
	v_mul_f32_e32 v75, v122, v135
	v_mul_f32_e32 v114, v123, v136
	v_mul_f32_e32 v119, v129, v137
	v_mul_f32_e32 v120, v138, v148
	v_mul_f32_e32 v121, v139, v149
	v_mul_f32_e32 v97, v145, v97
	v_mul_f32_e32 v69, v146, v69
	v_mul_f32_e32 v104, v147, v104
	v_mul_f32_e32 v70, v150, v70
	v_mul_f32_e32 v105, v151, v105
	v_mul_f32_e32 v71, v152, v71
	v_lshlrev_b32_e32 v132, 16, v76
	v_and_b32_e32 v76, 0xffff0000, v76
	v_lshlrev_b32_e32 v140, 16, v77
	v_and_b32_e32 v77, 0xffff0000, v77
	v_lshlrev_b32_e32 v141, 16, v78
	v_and_b32_e32 v78, 0xffff0000, v78
	v_lshlrev_b32_e32 v142, 16, v79
	v_and_b32_e32 v79, 0xffff0000, v79
	v_fma_f32 v106, v24, v109, v28
	v_fma_f32 v107, v25, v111, v29
	v_fma_f32 v109, v26, v113, v30
	v_fma_f32 v111, v27, v115, v31
	v_fma_f32 v113, v16, v126, v20
	v_fma_f32 v115, v17, v127, v21
	v_fma_f32 v124, v18, v130, v22
	v_fma_f32 v125, v19, v131, v23
	v_lshlrev_b32_e32 v122, 16, v64
	v_and_b32_e32 v123, 0xffff0000, v64
	v_lshlrev_b32_e32 v126, 16, v65
	v_and_b32_e32 v127, 0xffff0000, v65
	v_lshlrev_b32_e32 v129, 16, v66
	v_and_b32_e32 v130, 0xffff0000, v66
	v_lshlrev_b32_e32 v131, 16, v67
	v_and_b32_e32 v133, 0xffff0000, v67
	v_cvt_pk_bf16_f32 v64, v72, v73
	v_cvt_pk_bf16_f32 v65, v74, v75
	v_cvt_pk_bf16_f32 v66, v114, v119
	v_cvt_pk_bf16_f32 v67, v120, v121
	v_fmac_f32_e32 v88, v8, v96
	v_fmac_f32_e32 v89, v9, v68
	v_fmac_f32_e32 v108, v10, v97
	v_fmac_f32_e32 v110, v11, v69
	v_fmac_f32_e32 v112, v12, v104
	v_fmac_f32_e32 v116, v13, v70
	v_fmac_f32_e32 v117, v14, v105
	v_fmac_f32_e32 v118, v15, v71
	v_lshlrev_b32_e32 v72, 16, v60
	v_and_b32_e32 v60, 0xffff0000, v60
	v_lshlrev_b32_e32 v73, 16, v61
	v_and_b32_e32 v61, 0xffff0000, v61
	v_lshlrev_b32_e32 v74, 16, v62
	v_and_b32_e32 v62, 0xffff0000, v62
	v_lshlrev_b32_e32 v75, 16, v63
	v_and_b32_e32 v63, 0xffff0000, v63
	v_lshlrev_b32_e32 v114, 16, v56
	v_and_b32_e32 v56, 0xffff0000, v56
	v_lshlrev_b32_e32 v119, 16, v57
	v_and_b32_e32 v57, 0xffff0000, v57
	v_lshlrev_b32_e32 v120, 16, v58
	v_and_b32_e32 v58, 0xffff0000, v58
	v_lshlrev_b32_e32 v121, 16, v59
	v_and_b32_e32 v59, 0xffff0000, v59
	v_fmac_f32_e32 v106, v0, v96
	v_fmac_f32_e32 v107, v1, v68
	v_fmac_f32_e32 v109, v2, v97
	v_fmac_f32_e32 v111, v3, v69
	v_fmac_f32_e32 v113, v4, v104
	v_fmac_f32_e32 v115, v5, v70
	v_fmac_f32_e32 v124, v6, v105
	v_fmac_f32_e32 v125, v7, v71
	v_fma_f32 v96, v24, v96, v28
	v_fma_f32 v68, v25, v68, v29
	v_fma_f32 v97, v26, v97, v30
	v_fma_f32 v69, v27, v69, v31
	global_store_dwordx4 v[94:95], v[64:67], off
	v_mul_f32_e32 v79, v118, v79
	v_mul_f32_e32 v72, v72, v114
	v_mul_f32_e32 v64, v88, v132
	v_mul_f32_e32 v65, v89, v76
	v_mul_f32_e32 v66, v108, v140
	v_mul_f32_e32 v67, v110, v77
	v_mul_f32_e32 v76, v112, v141
	v_mul_f32_e32 v77, v116, v78
	v_mul_f32_e32 v78, v117, v142
	v_mul_f32_e32 v88, v60, v56
	v_mul_f32_e32 v73, v73, v119
	v_mul_f32_e32 v89, v61, v57
	v_mul_f32_e32 v74, v74, v120
	v_mul_f32_e32 v94, v62, v58
	v_mul_f32_e32 v75, v75, v121
	v_mul_f32_e32 v95, v63, v59
	v_lshlrev_b32_e32 v108, 16, v52
	v_and_b32_e32 v110, 0xffff0000, v52
	v_lshlrev_b32_e32 v112, 16, v53
	v_and_b32_e32 v114, 0xffff0000, v53
	v_lshlrev_b32_e32 v116, 16, v54
	v_and_b32_e32 v117, 0xffff0000, v54
	v_lshlrev_b32_e32 v118, 16, v55
	v_and_b32_e32 v119, 0xffff0000, v55
	v_lshlrev_b32_e32 v52, 16, v48
	v_and_b32_e32 v53, 0xffff0000, v48
	v_lshlrev_b32_e32 v54, 16, v49
	v_and_b32_e32 v55, 0xffff0000, v49
	v_lshlrev_b32_e32 v56, 16, v50
	v_and_b32_e32 v57, 0xffff0000, v50
	v_lshlrev_b32_e32 v58, 16, v51
	v_and_b32_e32 v59, 0xffff0000, v51
	v_cvt_pk_bf16_f32 v48, v64, v65
	v_cvt_pk_bf16_f32 v49, v66, v67
	v_cvt_pk_bf16_f32 v50, v76, v77
	v_cvt_pk_bf16_f32 v51, v78, v79
	v_lshlrev_b32_e32 v60, 16, v44
	v_and_b32_e32 v61, 0xffff0000, v44
	v_lshlrev_b32_e32 v44, 16, v45
	v_and_b32_e32 v45, 0xffff0000, v45
	v_fma_f32 v104, v16, v104, v20
	v_fma_f32 v70, v17, v70, v21
	v_fma_f32 v105, v18, v105, v22
	v_fma_f32 v71, v19, v71, v23
	v_fmac_f32_e32 v106, v8, v72
	v_fmac_f32_e32 v107, v9, v88
	v_fmac_f32_e32 v109, v10, v73
	v_fmac_f32_e32 v111, v11, v89
	v_fmac_f32_e32 v113, v12, v74
	v_fmac_f32_e32 v115, v13, v94
	v_fmac_f32_e32 v124, v14, v75
	v_fmac_f32_e32 v125, v15, v95
	v_lshlrev_b32_e32 v62, 16, v46
	v_and_b32_e32 v63, 0xffff0000, v46
	v_lshlrev_b32_e32 v64, 16, v47
	v_and_b32_e32 v65, 0xffff0000, v47
	v_fmac_f32_e32 v96, v0, v72
	v_fmac_f32_e32 v68, v1, v88
	v_fmac_f32_e32 v97, v2, v73
	v_fmac_f32_e32 v69, v3, v89
	global_store_dwordx4 v[92:93], v[48:51], off offset:-4096
	v_fmac_f32_e32 v104, v4, v74
	v_fmac_f32_e32 v70, v5, v94
	v_pk_mul_f32 v[50:51], v[52:53], v[60:61]
	v_pk_mul_f32 v[48:49], v[54:55], v[44:45]
	v_fmac_f32_e32 v105, v6, v75
	v_fmac_f32_e32 v71, v7, v95
	v_fma_f32 v66, v24, v72, v28
	v_fma_f32 v67, v25, v88, v29
	v_fma_f32 v72, v26, v73, v30
	v_fma_f32 v73, v27, v89, v31
	v_fma_f32 v76, v17, v94, v21
	v_fma_f32 v77, v19, v95, v23
	v_mul_f32_e32 v78, v106, v122
	v_mul_f32_e32 v79, v107, v123
	v_mul_f32_e32 v88, v109, v126
	v_mul_f32_e32 v89, v111, v127
	v_mul_f32_e32 v94, v113, v129
	v_mul_f32_e32 v95, v115, v130
	v_mul_f32_e32 v106, v124, v131
	v_mul_f32_e32 v107, v125, v133
	v_pk_mul_f32 v[46:47], v[56:57], v[62:63]
	v_pk_mul_f32 v[44:45], v[58:59], v[64:65]
	v_lshlrev_b32_e32 v64, 16, v40
	v_and_b32_e32 v65, 0xffff0000, v40
	v_lshlrev_b32_e32 v109, 16, v41
	v_and_b32_e32 v111, 0xffff0000, v41
	v_lshlrev_b32_e32 v113, 16, v42
	v_and_b32_e32 v115, 0xffff0000, v42
	v_lshlrev_b32_e32 v120, 16, v43
	v_and_b32_e32 v121, 0xffff0000, v43
	v_cvt_pk_bf16_f32 v40, v78, v79
	v_cvt_pk_bf16_f32 v41, v88, v89
	v_cvt_pk_bf16_f32 v42, v94, v95
	v_cvt_pk_bf16_f32 v43, v106, v107
	v_fmac_f32_e32 v96, v8, v50
	v_fmac_f32_e32 v68, v9, v51
	v_fmac_f32_e32 v97, v10, v48
	v_fmac_f32_e32 v69, v11, v49
	v_lshlrev_b32_e32 v52, 16, v36
	v_and_b32_e32 v53, 0xffff0000, v36
	v_lshlrev_b32_e32 v36, 16, v37
	v_and_b32_e32 v37, 0xffff0000, v37
	v_lshlrev_b32_e32 v56, 16, v32
	v_and_b32_e32 v57, 0xffff0000, v32
	v_lshlrev_b32_e32 v58, 16, v33
	v_and_b32_e32 v59, 0xffff0000, v33
	v_add_u32_e32 v103, 8, v103
	v_fma_f32 v74, v16, v74, v20
	v_fma_f32 v75, v18, v75, v22
	v_fmac_f32_e32 v104, v12, v46
	v_fmac_f32_e32 v70, v13, v47
	v_fmac_f32_e32 v105, v14, v44
	v_fmac_f32_e32 v71, v15, v45
	v_lshlrev_b32_e32 v54, 16, v38
	v_and_b32_e32 v55, 0xffff0000, v38
	v_lshlrev_b32_e32 v38, 16, v39
	v_and_b32_e32 v39, 0xffff0000, v39
	v_lshlrev_b32_e32 v60, 16, v34
	v_and_b32_e32 v61, 0xffff0000, v34
	v_lshlrev_b32_e32 v62, 16, v35
	v_and_b32_e32 v63, 0xffff0000, v35
	v_fmac_f32_e32 v66, v0, v50
	v_fmac_f32_e32 v67, v1, v51
	v_fmac_f32_e32 v72, v2, v48
	v_fmac_f32_e32 v73, v3, v49
	global_store_dwordx4 v[92:93], v[40:43], off
	v_pk_mul_f32 v[32:33], v[52:53], v[56:57]
	v_pk_mul_f32 v[34:35], v[36:37], v[58:59]
	v_mul_f32_e32 v40, v96, v108
	v_mul_f32_e32 v41, v68, v110
	v_mul_f32_e32 v42, v97, v112
	v_mul_f32_e32 v43, v69, v114
	v_cmp_ge_i32_e64 s[0:1], v103, v102
	v_fmac_f32_e32 v74, v4, v46
	v_fmac_f32_e32 v76, v5, v47
	v_fmac_f32_e32 v75, v6, v44
	v_fmac_f32_e32 v77, v7, v45
	v_mul_f32_e32 v68, v104, v116
	v_mul_f32_e32 v69, v70, v117
	v_mul_f32_e32 v70, v105, v118
	v_mul_f32_e32 v71, v71, v119
	v_pk_mul_f32 v[36:37], v[54:55], v[60:61]
	v_pk_mul_f32 v[38:39], v[38:39], v[62:63]
	v_cvt_pk_bf16_f32 v40, v40, v41
	v_cvt_pk_bf16_f32 v41, v42, v43
	v_cvt_pk_bf16_f32 v42, v68, v69
	v_cvt_pk_bf16_f32 v43, v70, v71
	v_fmac_f32_e32 v66, v8, v32
	v_fmac_f32_e32 v67, v9, v33
	v_fmac_f32_e32 v72, v10, v34
	v_fmac_f32_e32 v73, v11, v35
	v_lshl_add_u64 v[82:83], v[82:83], 0, s[10:11]
	v_lshl_add_u64 v[84:85], v[84:85], 0, s[12:13]
	s_or_b64 s[14:15], s[0:1], s[14:15]
	v_fmac_f32_e32 v74, v12, v36
	v_fmac_f32_e32 v76, v13, v37
	v_fmac_f32_e32 v75, v14, v38
	v_fmac_f32_e32 v77, v15, v39
	global_store_dwordx4 v[90:91], v[40:43], off
	v_mul_f32_e32 v52, v74, v113
	v_mul_f32_e32 v53, v76, v115
	v_mul_f32_e32 v40, v66, v64
	v_mul_f32_e32 v41, v67, v65
	v_mul_f32_e32 v42, v72, v109
	v_mul_f32_e32 v43, v73, v111
	v_mul_f32_e32 v54, v75, v120
	v_mul_f32_e32 v55, v77, v121
	v_cvt_pk_bf16_f32 v40, v40, v41
	v_cvt_pk_bf16_f32 v41, v42, v43
	v_cvt_pk_bf16_f32 v42, v52, v53
	v_cvt_pk_bf16_f32 v43, v54, v55
	global_store_dwordx4 v[86:87], v[40:43], off
	s_andn2_b64 exec, exec, s[14:15]
	s_cbranch_execnz .LBB0_248
	s_or_b64 exec, exec, s[14:15]
	v_add_u32_e32 v100, s16, v100
	v_cmp_lt_i32_e32 vcc, s28, v100
	s_or_b64 s[4:5], vcc, s[4:5]
	v_add_u32_e32 v101, s17, v101
	s_andn2_b64 exec, exec, s[4:5]
	s_cbranch_execnz .LBB0_245

.LBB0_253:
	s_or_b64 exec, exec, s[4:5]
	v_and_b32_e32 v18, 63, v128
	v_cmp_eq_u32_e64 s[4:5], 0, v18
	v_cmp_gt_u32_e64 s[6:7], 2, v18
	v_cmp_gt_u32_e64 s[8:9], 4, v18
	v_cmp_gt_u32_e64 s[10:11], 8, v18
	v_cmp_gt_u32_e64 s[12:13], 16, v18
	v_cmp_gt_u32_e64 s[14:15], 32, v18
	v_lshl_add_u32 v26, v18, 2, 16
	v_lshrrev_b32_e32 v18, 2, v128
	v_lshlrev_b32_e32 v20, 2, v128
	v_mov_b32_e32 v21, v17
	v_lshrrev_b32_e32 v28, 7, v128
	v_lshrrev_b32_e32 v34, 7, v34
	v_and_b32_e32 v47, 15, v128
	v_and_b32_e32 v18, 0xf0, v18
	v_lshl_add_u64 v[20:21], s[80:81], 0, v[20:21]
	s_mov_b64 s[24:25], 0x3ef00000
	v_xor_b32_e32 v28, v28, v128
	v_xor_b32_e32 v34, v34, v128
	v_or_b32_e32 v39, v18, v47
	v_lshrrev_b32_e32 v50, 1, v128
	v_lshl_add_u64 v[20:21], v[20:21], 0, s[24:25]
	v_and_b32_e32 v36, 7, v22
	v_lshlrev_b32_e32 v28, 3, v28
	s_movk_i32 s24, 0x48
	v_mov_b32_e32 v31, 0x120
	v_lshlrev_b32_e32 v34, 3, v34
	s_movk_i32 s22, 0x90
	v_and_b32_e32 v48, 24, v50
	v_bitop3_b32 v41, v18, 56, v47 bitop3:0xc8
	v_lshlrev_b32_e32 v18, 8, v39
	v_mov_b32_e32 v19, v17
	v_and_or_b32 v32, v28, 56, v36
	v_mul_u32_u24_e32 v37, 0x48, v35
	v_mov_b32_e32 v30, 0x90
	v_mad_u32_u24 v42, v35, s24, v31
	v_mov_b32_e32 v33, 0x1b0
	v_and_or_b32 v44, v34, 56, v36
	v_bitop3_b32 v45, v47, 24, 16 bitop3:0xc8
	v_mad_u32_u24 v40, v39, s22, 16
	v_lshl_add_u64 v[18:19], s[78:79], 0, v[18:19]
	v_mov_b32_e32 v49, v17
	v_or_b32_e32 v28, v32, v37
	v_mad_u32_u24 v38, v35, s24, v30
	v_add_u32_e32 v31, v32, v42
	v_mad_u32_u24 v43, v35, s24, v33
	v_or_b32_e32 v34, v44, v37
	v_add_u32_e32 v37, v44, v42
	v_bitop3_b32 v39, v39, v48, 56 bitop3:0x6c
	v_bitop3_b32 v41, v48, v41, 32 bitop3:0x36
	v_and_b32_e32 v42, 8, v128
	v_bitop3_b32 v45, v48, v45, 32 bitop3:0x36
	v_bitop3_b32 v52, v47, 40, 32 bitop3:0xc8
	v_bitop3_b32 v57, v47, 56, 48 bitop3:0xc8
	v_lshl_add_u64 v[18:19], v[18:19], 0, v[48:49]
	v_mad_u32_u24 v29, v35, s24, v32
	v_add_u32_e32 v30, v32, v38
	v_add_u32_e32 v32, v32, v43
	v_add_u32_e32 v36, v44, v38
	v_add_u32_e32 v38, v44, v43
	v_lshl_add_u32 v39, v39, 1, v40
	v_lshl_add_u32 v40, v41, 1, v40
	v_mad_u32_u24 v53, v47, s22, 16
	v_bitop3_b32 v41, v50, v42, 24 bitop3:0x6c
	v_bitop3_b32 v42, v48, v42, 32 bitop3:0x36
	v_or_b32_e32 v43, 16, v47
	v_lshlrev_b32_e32 v51, 1, v45
	v_bitop3_b32 v45, v50, v52, 24 bitop3:0x6c
	v_bitop3_b32 v52, v48, v52, 32 bitop3:0x36
	v_bitop3_b32 v47, v50, v57, 24 bitop3:0x6c
	v_bitop3_b32 v48, v48, v57, 32 bitop3:0x36
	v_bitop3_b32 v43, v50, v43, 24 bitop3:0x28
	v_add_u32_e32 v56, 0x1b00, v53
	v_lshlrev_b32_e32 v58, 1, v47
	v_lshlrev_b32_e32 v57, 1, v48
	v_mad_u32_u24 v35, v35, s24, v44
	v_add_u32_e32 v44, 0x900, v53
	v_lshlrev_b32_e32 v49, 1, v43
	v_add_u32_e32 v46, 0x1200, v53
	v_lshlrev_b32_e32 v54, 1, v45
	v_add_u32_e32 v47, v56, v58
	v_add_u32_e32 v48, v56, v57
	v_add_u32_e32 v50, 0x2d00, v53
	v_add_u32_e32 v56, 0x3600, v53
	s_add_u32 s31, s80, 0x3f100000
	v_add_u32_e32 v43, v44, v49
	v_add_u32_e32 v44, v44, v51
	v_add_u32_e32 v45, v46, v54
	v_lshlrev_b32_e32 v52, 1, v52
	v_add_u32_e32 v49, v50, v49
	v_add_u32_e32 v50, v50, v51
	v_add_u32_e32 v51, v56, v54
	v_add_u32_e32 v54, 0x3f00, v53
	s_addc_u32 s34, s81, 0
	v_mad_u32_u24 v62, v128, s22, 16
	v_and_b32_e32 v55, 56, v128
	v_lshl_add_u32 v41, v41, 1, v53
	v_lshl_add_u32 v42, v42, 1, v53
	v_add_u32_e32 v46, v46, v52
	v_add_u32_e32 v52, v56, v52
	v_add_u32_e32 v53, v54, v58
	v_add_u32_e32 v54, v54, v57
	v_bitop3_b32 v56, v128, 8, 56 bitop3:0x6c
	v_bitop3_b32 v57, v128, 16, 56 bitop3:0x6c
	v_bitop3_b32 v58, v128, 24, 56 bitop3:0x6c
	v_bitop3_b32 v59, v128, 32, 56 bitop3:0x6c
	v_bitop3_b32 v60, v128, 40, 56 bitop3:0x6c
	v_bitop3_b32 v61, v128, 48, 56 bitop3:0x6c
	v_bitop3_b32 v63, v128, 56, v128 bitop3:0xc
	s_add_u32 s35, s80, 0x3f110000
	v_lshl_add_u32 v55, v55, 1, v62
	v_lshl_add_u32 v56, v56, 1, v62
	v_lshl_add_u32 v57, v57, 1, v62
	v_lshl_add_u32 v58, v58, 1, v62
	v_lshl_add_u32 v59, v59, 1, v62
	v_lshl_add_u32 v60, v60, 1, v62
	v_lshl_add_u32 v61, v61, 1, v62
	v_lshl_add_u32 v62, v63, 1, v62
	v_mbcnt_lo_u32_b32 v63, -1, 0
	s_addc_u32 s36, s81, 0
	s_movk_i32 s16, 0x80
	s_add_i32 s22, s33, s84
	v_mbcnt_hi_u32_b32 v63, -1, v63
	v_bfrev_b32_e32 v64, 0.5
	v_cmp_gt_u32_e64 s[16:17], s16, v128
	v_lshl_add_u32 v27, v22, 2, 16
	v_lshl_add_u32 v28, v28, 1, 16
	v_lshl_add_u32 v29, v29, 1, 16
	v_lshl_add_u32 v30, v30, 1, 16
	v_lshl_add_u32 v31, v31, 1, 16
	v_lshl_add_u32 v32, v32, 1, 16
	v_lshl_add_u32 v33, v23, 2, 16
	v_lshl_add_u32 v34, v34, 1, 16
	v_lshl_add_u32 v35, v35, 1, 16
	v_lshl_add_u32 v36, v36, 1, 16
	v_lshl_add_u32 v37, v37, 1, 16
	v_lshl_add_u32 v38, v38, 1, 16
	s_lshl_b32 s37, s22, 3
	s_lshl_b32 s38, s84, 3
	s_lshl_b32 s39, s22, 6
	s_lshl_b32 s40, s84, 6
	v_lshl_or_b32 v64, v63, 2, v64
	v_mov_b32_e32 v65, 16
	s_mov_b32 s24, s33
	s_waitcnt vmcnt(0)
	s_branch .LBB0_255

.LBB0_255:
	s_and_saveexec_b64 s[26:27], s[2:3]
	s_cbranch_execz .LBB0_258
	s_waitcnt vmcnt(8)
	v_mov_b32_e32 v66, v25
	s_nop 4
	s_nop 1
	v_add_f32_dpp v66, v66, v66 row_shr:1 row_mask:0xf bank_mask:0xf
	s_nop 1
	v_add_f32_dpp v66, v66, v66 row_shr:2 row_mask:0xf bank_mask:0xf
	s_nop 1
	v_add_f32_dpp v66, v66, v66 row_shr:4 row_mask:0xf bank_mask:0xf
	s_nop 1
	v_add_f32_dpp v66, v66, v66 row_shr:8 row_mask:0xf bank_mask:0xf
	s_nop 1
	v_add_f32_dpp v66, v66, v66 row_bcast:15 row_mask:0xa bank_mask:0xf
	s_nop 1
	v_add_f32_dpp v66, v66, v66 row_bcast:31 row_mask:0xc bank_mask:0xf
	s_nop 1
	v_readlane_b32 s98, v66, 63
	s_nop 1
	v_sub_f32_e32 v68, s98, v66
	v_add_f32_e32 v68, v24, v68
	v_mov_b32_e32 v69, v68
	s_nop 1
	v_max_f32_dpp v69, v69, v69 row_shr:1 row_mask:0xf bank_mask:0xf
	s_nop 1
	v_max_f32_dpp v69, v69, v69 row_shr:2 row_mask:0xf bank_mask:0xf
	s_nop 1
	v_max_f32_dpp v69, v69, v69 row_shr:4 row_mask:0xf bank_mask:0xf
	s_nop 1
	v_max_f32_dpp v69, v69, v69 row_shr:8 row_mask:0xf bank_mask:0xf
	s_nop 1
	v_max_f32_dpp v69, v69, v69 row_bcast:15 row_mask:0xa bank_mask:0xf
	s_nop 1
	v_max_f32_dpp v69, v69, v69 row_bcast:31 row_mask:0xc bank_mask:0xf
	s_nop 1
	v_readlane_b32 s99, v69, 63
	v_mov_b32_e32 v66, s98
	s_nop 0
	v_mov_b32_e32 v67, s99
	v_sub_f32_e32 v68, v68, v67
	v_mul_f32_e32 v68, 0x3fb8aa3b, v68
	v_exp_f32_e32 v68, v68
	ds_write_b32 v26, v68 offset:36864
	s_and_b64 exec, exec, s[4:5]
	s_cbranch_execz .LBB0_258
	s_ashr_i32 s25, s24, 31
	s_lshl_b64 s[28:29], s[24:25], 2
	s_add_u32 s42, s31, s28
	s_addc_u32 s43, s34, s29
	s_add_u32 s28, s35, s28
	s_addc_u32 s29, s36, s29
	global_store_dword v17, v67, s[42:43]
	global_store_dword v17, v66, s[28:29]
.LBB0_258:
	s_or_b64 exec, exec, s[26:27]
	s_waitcnt vmcnt(8) lgkmcnt(0)
	s_barrier
	ds_read_b32 v66, v27 offset:36864
	v_lshlrev_b32_e32 v67, 16, v0
	v_and_b32_e32 v68, 0xffff0000, v0
	v_lshlrev_b32_e32 v75, 16, v4
	v_lshlrev_b32_e32 v69, 16, v1
	v_and_b32_e32 v76, 0xffff0000, v4
	v_lshlrev_b32_e32 v77, 16, v5
	v_cvt_pk_bf16_f32 v67, v67, v68
	ds_read_b32 v68, v33 offset:36864
	s_waitcnt lgkmcnt(1)
	v_mul_f32_e32 v75, v66, v75
	v_and_b32_e32 v70, 0xffff0000, v1
	v_and_b32_e32 v78, 0xffff0000, v5
	v_mul_f32_e32 v76, v66, v76
	v_cvt_pk_bf16_f32 v75, v75, v76
	ds_write_b16 v28, v67
	ds_write_b16_d16_hi v29, v67 offset:144
	ds_write_b16 v28, v75 offset:18432
	ds_write_b16_d16_hi v29, v75 offset:18576
	v_cvt_pk_bf16_f32 v67, v69, v70
	v_mul_f32_e32 v69, v66, v77
	v_lshlrev_b32_e32 v79, 16, v6
	v_mul_f32_e32 v70, v66, v78
	v_cvt_pk_bf16_f32 v69, v69, v70
	v_and_b32_e32 v80, 0xffff0000, v6
	ds_write_b16 v29, v67 offset:288
	ds_write_b16_d16_hi v30, v67 offset:144
	ds_write_b16 v29, v69 offset:18720
	ds_write_b16_d16_hi v30, v69 offset:18576
	v_mul_f32_e32 v69, v66, v79
	v_lshlrev_b32_e32 v71, 16, v2
	v_and_b32_e32 v72, 0xffff0000, v2
	v_lshlrev_b32_e32 v81, 16, v7
	v_and_b32_e32 v82, 0xffff0000, v7
	v_cvt_pk_bf16_f32 v67, v71, v72
	v_mul_f32_e32 v70, v66, v80
	v_cvt_pk_bf16_f32 v69, v69, v70
	ds_write_b16 v29, v67 offset:576
	ds_write_b16_d16_hi v31, v67 offset:144
	ds_write_b16 v29, v69 offset:19008
	ds_write_b16_d16_hi v31, v69 offset:18576
	v_mul_f32_e32 v69, v66, v81
	v_mul_f32_e32 v66, v66, v82
	v_lshlrev_b32_e32 v73, 16, v3
	v_and_b32_e32 v74, 0xffff0000, v3
	v_cvt_pk_bf16_f32 v67, v73, v74
	v_cvt_pk_bf16_f32 v66, v69, v66
	ds_write_b16 v29, v67 offset:864
	ds_write_b16_d16_hi v32, v67 offset:144
	ds_write_b16 v29, v66 offset:19296
	ds_write_b16_d16_hi v32, v66 offset:18576
	v_lshlrev_b32_e32 v66, 16, v8
	v_and_b32_e32 v67, 0xffff0000, v8
	v_lshlrev_b32_e32 v75, 16, v12
	v_and_b32_e32 v76, 0xffff0000, v12
	v_cvt_pk_bf16_f32 v66, v66, v67
	s_waitcnt lgkmcnt(14)
	v_mul_f32_e32 v67, v68, v75
	v_lshlrev_b32_e32 v77, 16, v13
	v_mul_f32_e32 v75, v68, v76
	v_cvt_pk_bf16_f32 v67, v67, v75
	v_lshlrev_b32_e32 v69, 16, v9
	v_and_b32_e32 v78, 0xffff0000, v13
	ds_write_b16 v34, v66
	ds_write_b16_d16_hi v35, v66 offset:144
	ds_write_b16 v34, v67 offset:18432
	ds_write_b16_d16_hi v35, v67 offset:18576
	v_mul_f32_e32 v67, v68, v77
	v_and_b32_e32 v70, 0xffff0000, v9
	v_lshlrev_b32_e32 v79, 16, v14
	v_cvt_pk_bf16_f32 v66, v69, v70
	v_mul_f32_e32 v69, v68, v78
	v_cvt_pk_bf16_f32 v67, v67, v69
	s_add_i32 s41, s24, s84
	v_and_b32_e32 v80, 0xffff0000, v14
	ds_write_b16 v35, v66 offset:288
	ds_write_b16_d16_hi v36, v66 offset:144
	ds_write_b16 v35, v67 offset:18720
	ds_write_b16_d16_hi v36, v67 offset:18576
	v_mul_f32_e32 v67, v68, v79
	s_cmpk_gt_i32 s41, 0xfff
	v_lshlrev_b32_e32 v71, 16, v10
	v_and_b32_e32 v72, 0xffff0000, v10
	v_lshlrev_b32_e32 v81, 16, v15
	v_cvt_pk_bf16_f32 v66, v71, v72
	v_mul_f32_e32 v69, v68, v80
	v_cvt_pk_bf16_f32 v67, v67, v69
	s_cselect_b64 s[26:27], -1, 0
	v_lshlrev_b32_e32 v73, 16, v11
	v_and_b32_e32 v74, 0xffff0000, v11
	v_and_b32_e32 v82, 0xffff0000, v15
	ds_write_b16 v35, v66 offset:576
	ds_write_b16_d16_hi v37, v66 offset:144
	ds_write_b16 v35, v67 offset:19008
	ds_write_b16_d16_hi v37, v67 offset:18576
	v_cvt_pk_bf16_f32 v66, v73, v74
	v_mul_f32_e32 v67, v68, v81
	s_and_b64 vcc, exec, s[26:27]
	v_mul_f32_e32 v68, v68, v82
	v_cvt_pk_bf16_f32 v67, v67, v68
	ds_write_b16 v35, v66 offset:864
	ds_write_b16_d16_hi v38, v66 offset:144
	ds_write_b16 v35, v67 offset:19296
	ds_write_b16_d16_hi v38, v67 offset:18576
	s_cbranch_vccnz .LBB0_262
	s_and_b32 s22, s37, 0xffffc000
	s_and_b32 s28, s39, 0x3fc0
	s_or_b32 s42, s22, s28
	s_bfe_u32 s25, s41, 0x30008
	v_or_b32_e32 v0, s42, v22
	v_mov_b64_e32 v[8:9], s[20:21]
	v_mad_i64_i32 v[0:1], s[28:29], v0, s30, v[8:9]
	s_lshl_b32 s22, s25, 8
	v_lshl_add_u64 v[0:1], v[0:1], 0, s[22:23]
	v_add_u32_e32 v10, s42, v23
	v_lshl_add_u64 v[0:1], v[0:1], 0, v[16:17]
	v_mad_i64_i32 v[8:9], s[28:29], v10, s30, v[8:9]
	v_add_co_u32_e32 v4, vcc, 0x2000, v0
	v_lshl_add_u64 v[8:9], v[8:9], 0, s[22:23]
	s_nop 0
	v_addc_co_u32_e32 v5, vcc, 0, v1, vcc
	v_lshl_add_u64 v[8:9], v[8:9], 0, v[16:17]
	v_add_co_u32_e32 v12, vcc, 0x2000, v8
	global_load_dwordx4 v[0:3], v[4:5], off
	s_nop 0
	global_load_dwordx4 v[4:7], v[4:5], off offset:2048
	v_addc_co_u32_e32 v13, vcc, 0, v9, vcc
	global_load_dwordx4 v[8:11], v[12:13], off
	s_nop 0
	global_load_dwordx4 v[12:15], v[12:13], off offset:2048
	s_and_saveexec_b64 s[28:29], s[2:3]
	s_cbranch_execz .LBB0_261
	v_or_b32_e32 v24, s42, v128
	v_ashrrev_i32_e32 v25, 31, v24
	v_lshlrev_b64 v[24:25], 6, v[24:25]
	v_lshl_add_u64 v[24:25], s[0:1], 0, v[24:25]
	s_lshl_b32 s22, s25, 2
	v_lshl_add_u64 v[66:67], v[24:25], 0, s[22:23]
	global_load_dword v24, v[66:67], off
	global_load_dword v25, v[66:67], off offset:32

.LBB0_569:
	v_and_b32_e32 v47, 63, v128
	v_cmp_eq_u32_e64 s[4:5], 0, v47
	v_cmp_gt_u32_e64 s[6:7], 2, v47
	v_cmp_gt_u32_e64 s[8:9], 4, v47
	v_cmp_gt_u32_e64 s[10:11], 8, v47
	v_cmp_gt_u32_e64 s[12:13], 16, v47
	v_cmp_gt_u32_e64 s[14:15], 32, v47
	s_add_i32 s42, 16, 0x17c00
	v_lshlrev_b32_e32 v47, 2, v47
	s_add_i32 s18, 16, 0x17d00
	s_add_i32 s43, 16, 0x17e00
	s_add_i32 s54, 16, 0x17f00
	s_add_i32 s62, 16, 0x18000
	s_add_i32 s64, 16, 0x18200
	s_add_i32 s65, 16, 0x18300
	v_lshrrev_b32_e32 v45, 7, v45
	v_add_u32_e32 v112, s42, v47
	v_add_u32_e32 v113, s18, v47
	v_add_u32_e32 v114, s43, v47
	v_add_u32_e32 v115, s54, v47
	v_add_u32_e32 v116, s62, v47
	v_add_u32_e32 v117, s64, v47
	v_add_u32_e32 v118, s65, v47
	v_lshrrev_b32_e32 v47, 7, v128
	v_xor_b32_e32 v45, v45, v128
	v_lshl_add_u32 v52, v48, 1, 16
	v_lshl_or_b32 v53, v47, 4, v110
	v_and_b32_e32 v63, 7, v129
	v_mul_u32_u24_e32 v65, 0x88, v129
	v_mul_u32_u24_e32 v48, 0x48, v48
	v_lshlrev_b32_e32 v45, 3, v45
	v_lshlrev_b32_e32 v54, 2, v53
	v_and_b32_e32 v56, 48, v128
	v_lshrrev_b32_e32 v58, 3, v128
	s_add_i32 s68, 16, 0x18100
	v_lshl_add_u32 v127, v65, 1, v52
	v_xor_b32_e32 v65, v47, v128
	v_lshlrev_b32_e32 v48, 1, v48
	v_and_or_b32 v45, v45, 56, v63
	s_add_i32 s19, 16, 0x18400
	v_add_u32_e32 v120, s18, v54
	v_add_u32_e32 v57, 16, v56
	s_movk_i32 s18, 0x110
	s_movk_i32 s20, 0x90
	v_and_b32_e32 v59, 7, v128
	v_mul_u32_u24_e32 v60, 0x110, v58
	v_lshl_add_u32 v125, v58, 2, s68
	v_or_b32_e32 v58, v50, v110
	v_lshlrev_b32_e32 v65, 3, v65
	v_add_u32_e32 v66, 16, v48
	v_lshlrev_b32_e32 v45, 1, v45
	v_lshl_add_u32 v119, v128, 2, s19
	v_mad_u32_u24 v121, v53, s18, v57
	v_lshlrev_b32_e32 v61, 5, v59
	v_lshl_add_u32 v124, v59, 6, s19
	v_cmp_eq_u32_e64 s[18:19], 0, v59
	v_mad_u32_u24 v59, v58, s20, 16
	v_and_or_b32 v65, v65, 56, v63
	v_add3_u32 v133, 16, v45, v48
	v_add_u32_e32 v134, v66, v45
	v_mul_u32_u24_e32 v45, 0x110, v129
	s_mov_b32 s20, 0xd000
	v_lshlrev_b32_e32 v49, 1, v49
	v_lshlrev_b32_e32 v65, 1, v65
	v_add3_u32 v135, v52, v45, s20
	v_add_u32_e32 v45, 0x600, v128
	v_bfe_u32 v51, v128, 4, 2
	v_and_b32_e32 v49, 2, v49
	v_add3_u32 v130, 16, v65, v48
	v_add_u32_e32 v131, v66, v65
	v_mul_u32_u24_e32 v65, 0x88, v111
	v_lshrrev_b32_e32 v45, 4, v45
	v_lshlrev_b32_e32 v55, 2, v51
	v_lshl_add_u32 v132, v65, 1, v52
	v_mul_u32_u24_e32 v65, 0x110, v45
	v_lshlrev_b32_e32 v45, 4, v49
	v_or_b32_e32 v48, v45, v55
	v_or_b32_e32 v67, 2, v48
	v_add_u32_e32 v122, s62, v54
	v_mul_u32_u24_e32 v54, 0x90, v53
	s_add_i32 s30, 16, 0x15800
	v_or_b32_e32 v66, v45, v110
	v_cmp_le_u32_e64 s[22:23], v48, v53
	v_lshl_add_u32 v136, v48, 2, s42
	v_cmp_lt_u32_e64 s[24:25], v48, v53
	v_cmp_le_u32_e64 s[26:27], v67, v53
	v_lshl_add_u32 v137, v67, 2, s42
	v_or_b32_e32 v67, 3, v48
	v_lshlrev_b32_e32 v48, 1, v48
	v_or_b32_e32 v45, 16, v45
	v_add3_u32 v139, s30, v54, v48
	v_or_b32_e32 v48, v45, v55
	v_or_b32_e32 v45, v45, v110
	v_mul_u32_u24_e32 v54, 0x110, v45
	v_or_b32_e32 v45, 2, v48
	v_lshlrev_b32_e32 v51, 3, v51
	v_cmp_le_u32_e64 s[38:39], v45, v53
	v_lshl_add_u32 v141, v45, 2, s42
	v_or_b32_e32 v45, 3, v48
	v_add3_u32 v123, 16, v60, v61
	v_bitop3_b32 v60, v50, 56, v110 bitop3:0xc8
	v_cmp_le_u32_e64 s[40:41], v45, v53
	v_lshl_add_u32 v142, v45, 2, s42
	v_bitop3_b32 v45, v58, v51, 56 bitop3:0x6c
	v_lshl_add_u32 v143, v45, 1, v59
	v_bitop3_b32 v45, v51, v60, 32 bitop3:0x36
	v_or_b32_e32 v150, 16, v110
	v_lshl_add_u32 v144, v45, 1, v59
	v_lshlrev_b32_e32 v45, 2, v150
	v_or_b32_e32 v157, 32, v110
	v_add_u32_e32 v151, s43, v45
	v_add_u32_e32 v152, s62, v45
	v_add_u32_e32 v153, s68, v45
	v_add_u32_e32 v154, s54, v45
	v_add_u32_e32 v155, s65, v45
	v_add_u32_e32 v156, s64, v45
	v_lshlrev_b32_e32 v45, 2, v157
	v_or_b32_e32 v164, 48, v110
	v_mov_b32_e32 v89, 0
	v_add_u32_e32 v158, s43, v45
	v_add_u32_e32 v159, s62, v45
	v_add_u32_e32 v160, s68, v45
	v_add_u32_e32 v161, s54, v45
	v_add_u32_e32 v162, s65, v45
	v_add_u32_e32 v163, s64, v45
	v_lshlrev_b32_e32 v45, 2, v164
	v_add_u32_e32 v165, s43, v45
	v_add_u32_e32 v166, s62, v45
	v_add_u32_e32 v167, s68, v45
	v_add_u32_e32 v168, s54, v45
	v_add_u32_e32 v169, s65, v45
	v_add_u32_e32 v170, s64, v45
	v_mov_b32_e32 v45, v89
	v_mov_b32_e32 v88, v84
	v_lshl_add_u64 v[96:97], s[0:1], 0, v[44:45]
	v_mbcnt_lo_u32_b32 v44, -1, 0
	v_add_u32_e32 v62, s30, v56
	v_cmp_le_u32_e64 s[20:21], v49, v47
	v_cmp_lt_u32_e64 s[30:31], v49, v47
	v_cmp_le_u32_e64 s[34:35], v48, v53
	v_lshl_add_u32 v140, v48, 2, s42
	v_cmp_lt_u32_e64 s[36:37], v48, v53
	v_lshl_add_u64 v[48:49], s[74:75], 0, v[88:89]
	v_mov_b32_e32 v47, v89
	v_mbcnt_hi_u32_b32 v44, -1, v44
	v_lshl_add_u64 v[94:95], v[48:49], 0, v[46:47]
	v_and_b32_e32 v46, 64, v44
	v_xor_b32_e32 v45, 16, v44
	v_add_u32_e32 v47, 64, v46
	v_cmp_lt_i32_e32 vcc, v45, v47
	s_movk_i32 s16, 0x80
	v_lshl_add_u32 v61, v58, 7, v59
	v_cndmask_b32_e32 v45, v44, v45, vcc
	v_lshlrev_b32_e32 v84, 2, v45
	v_xor_b32_e32 v45, 32, v44
	v_cmp_lt_i32_e32 vcc, v45, v47
	v_or_b32_e32 v50, v55, v50
	v_lshlrev_b32_e32 v64, 2, v110
	v_cndmask_b32_e32 v45, v44, v45, vcc
	v_lshlrev_b32_e32 v171, 2, v45
	v_add_u32_e32 v45, -1, v44
	v_cmp_lt_i32_e32 vcc, v45, v46
	v_mul_u32_u24_e32 v63, 0x110, v111
	v_mul_u32_u24_e32 v66, 0x110, v66
	v_cndmask_b32_e32 v45, v45, v44, vcc
	v_lshlrev_b32_e32 v172, 2, v45
	v_add_u32_e32 v45, -2, v44
	v_cmp_lt_i32_e32 vcc, v45, v46
	v_cmp_le_u32_e64 s[28:29], v67, v53
	v_mul_u32_u24_e32 v51, 0x90, v110
	v_cndmask_b32_e32 v45, v45, v44, vcc
	v_lshlrev_b32_e32 v173, 2, v45
	v_add_u32_e32 v45, -4, v44
	v_cmp_lt_i32_e32 vcc, v45, v46
	v_mul_u32_u24_e32 v53, 0x110, v110
	v_mov_b32_e32 v77, v89
	v_cndmask_b32_e32 v45, v45, v44, vcc
	v_lshlrev_b32_e32 v174, 2, v45
	v_add_u32_e32 v45, -8, v44
	v_cmp_lt_i32_e32 vcc, v45, v46
	s_mov_b32 s55, 0
	v_cmp_gt_u32_e64 s[16:17], s16, v128
	v_cndmask_b32_e32 v45, v45, v44, vcc
	v_lshlrev_b32_e32 v175, 2, v45
	v_add_u32_e32 v45, -16, v44
	v_cmp_lt_i32_e32 vcc, v45, v46
	v_add_u32_e32 v126, s64, v64
	v_lshl_add_u32 v138, v67, 2, s42
	v_cndmask_b32_e32 v45, v45, v44, vcc
	v_lshlrev_b32_e32 v176, 2, v45
	v_subrev_u32_e32 v45, 32, v44
	v_cmp_lt_i32_e32 vcc, v45, v46
	s_and_b64 s[56:57], s[12:13], s[20:21]
	s_and_b64 s[60:61], s[12:13], s[30:31]
	v_cndmask_b32_e32 v45, v45, v44, vcc
	v_lshlrev_b32_e32 v177, 2, v45
	v_xor_b32_e32 v45, 1, v44
	v_cmp_lt_i32_e32 vcc, v45, v47
	v_add_u32_e32 v145, s43, v64
	v_add_u32_e32 v146, s62, v64
	v_cndmask_b32_e32 v45, v44, v45, vcc
	v_lshlrev_b32_e32 v178, 2, v45
	v_xor_b32_e32 v45, 2, v44
	v_cmp_lt_i32_e32 vcc, v45, v47
	v_add_u32_e32 v147, s68, v64
	v_add_u32_e32 v148, s54, v64
	v_cndmask_b32_e32 v45, v44, v45, vcc
	v_lshlrev_b32_e32 v179, 2, v45
	v_xor_b32_e32 v45, 4, v44
	v_cmp_lt_i32_e32 vcc, v45, v47
	v_add_u32_e32 v149, s65, v64
	v_lshl_add_u64 v[92:93], s[78:79], 0, v[76:77]
	v_cndmask_b32_e32 v44, v44, v45, vcc
	v_lshlrev_b32_e32 v180, 2, v44
	s_lshl_b32 s68, s84, 3
	s_lshl_b32 s69, s100, 6
	s_lshl_b32 s70, s84, 6
	v_add_u32_e32 v181, v52, v63
	v_add_u32_e32 v182, v52, v65
	s_movk_i32 s71, 0x3800
	s_movk_i32 s72, 0x1000
	s_movk_i32 s73, 0x2000
	s_movk_i32 s74, 0x4000
	s_movk_i32 s75, 0x3000
	v_add_u32_e32 v183, v57, v66
	v_add_u32_e32 v184, v57, v54
	v_add_u32_e32 v185, v61, v56
	s_brev_b32 s62, 60
	s_mov_b32 s82, 0x800000
	v_lshlrev_b32_e32 v88, 1, v50
	s_brev_b32 s83, 36
	v_add_u32_e32 v186, v62, v51
	v_add_u32_e32 v187, v57, v53
	s_mov_b32 s87, s100
	s_mov_b64 s[98:99], 0
	v_mov_b32_e32 v214, v79
	v_mov_b32_e32 v215, v75
	s_waitcnt vmcnt(0)
	s_branch .LBB0_571

.LBB0_571:
	v_cndmask_b32_e64 v31, v31, 0, s[98:99]
	v_cndmask_b32_e64 v30, v30, 0, s[98:99]
	v_cndmask_b32_e64 v29, v29, 0, s[98:99]
	v_cndmask_b32_e64 v28, v28, 0, s[98:99]
	v_cndmask_b32_e64 v35, v35, 0, s[98:99]
	v_cndmask_b32_e64 v34, v34, 0, s[98:99]
	v_cndmask_b32_e64 v33, v33, 0, s[98:99]
	v_cndmask_b32_e64 v32, v32, 0, s[98:99]
	v_cndmask_b32_e64 v39, v39, 0, s[98:99]
	v_cndmask_b32_e64 v38, v38, 0, s[98:99]
	v_cndmask_b32_e64 v37, v37, 0, s[98:99]
	v_cndmask_b32_e64 v36, v36, 0, s[98:99]
	v_cndmask_b32_e64 v43, v43, 0, s[98:99]
	v_cndmask_b32_e64 v42, v42, 0, s[98:99]
	v_cndmask_b32_e64 v41, v41, 0, s[98:99]
	v_cndmask_b32_e64 v40, v40, 0, s[98:99]
	v_cndmask_b32_e64 v75, v215, 0, s[98:99]
	v_cndmask_b32_e64 v79, v214, 0, s[98:99]
	s_and_saveexec_b64 s[0:1], s[2:3]
	s_cbranch_execz .LBB0_573
	s_waitcnt vmcnt(4)
	ds_write_b32 v116, v89
	ds_write_b32 v117, v89
	v_max_f32_e32 v48, v79, v79
	v_mov_b32_e32 v44, v73
	s_nop 4
	s_nop 1
	v_add_f32_dpp v44, v44, v44 row_shr:1 row_mask:0xf bank_mask:0xf
	s_nop 1
	v_add_f32_dpp v44, v44, v44 row_shr:2 row_mask:0xf bank_mask:0xf
	s_nop 1
	v_add_f32_dpp v44, v44, v44 row_shr:4 row_mask:0xf bank_mask:0xf
	s_nop 1
	v_add_f32_dpp v44, v44, v44 row_shr:8 row_mask:0xf bank_mask:0xf
	s_nop 1
	v_add_f32_dpp v44, v44, v44 row_bcast:15 row_mask:0xa bank_mask:0xf
	s_nop 1
	v_add_f32_dpp v44, v44, v44 row_bcast:31 row_mask:0xc bank_mask:0xf
	v_sub_f32_e32 v45, v85, v44
	v_mov_b32_e32 v46, v45
	s_nop 1
	v_max_f32_dpp v46, v46, v46 row_shr:1 row_mask:0xf bank_mask:0xf
	s_nop 1
	v_max_f32_dpp v46, v46, v46 row_shr:2 row_mask:0xf bank_mask:0xf
	s_nop 1
	v_max_f32_dpp v46, v46, v46 row_shr:4 row_mask:0xf bank_mask:0xf
	s_nop 1
	v_max_f32_dpp v46, v46, v46 row_shr:8 row_mask:0xf bank_mask:0xf
	s_nop 1
	v_max_f32_dpp v46, v46, v46 row_bcast:15 row_mask:0xa bank_mask:0xf
	s_nop 1
	v_max_f32_dpp v46, v46, v46 row_bcast:31 row_mask:0xc bank_mask:0xf
	v_max_f32_e32 v46, v46, v46
	v_max_f32_e32 v46, v48, v46
	v_sub_f32_e32 v47, v79, v46
	v_add_f32_e32 v44, v44, v46
	v_mul_f32_e32 v47, 0x3fb8aa3b, v47
	v_mul_f32_e32 v44, 0xbfb8aa3b, v44
	v_exp_f32_e32 v47, v47
	v_exp_f32_e32 v44, v44
	ds_write_b32 v112, v45
	ds_write_b32 v113, v46
	ds_write_b32 v114, v47
	ds_write_b32 v115, v44
	ds_write_b32 v118, v89
.LBB0_573:
	s_or_b64 exec, exec, s[0:1]
	ds_write_b128 v127, v[0:3]
	ds_write_b128 v127, v[4:7] offset:17408
	ds_write_b16 v130, v8 offset:34816
	ds_write_b16_d16_hi v131, v8 offset:34960
	ds_write_b16 v130, v9 offset:35104
	ds_write_b16_d16_hi v131, v9 offset:35248
	ds_write_b16 v130, v10 offset:35392
	ds_write_b16_d16_hi v131, v10 offset:35536
	ds_write_b16 v130, v11 offset:35680
	ds_write_b16_d16_hi v131, v11 offset:35824
	ds_write_b128 v132, v[12:15]
	ds_write_b128 v132, v[16:19] offset:17408
	ds_write_b16 v133, v20 offset:34816
	ds_write_b16_d16_hi v134, v20 offset:34960
	ds_write_b16 v133, v21 offset:35104
	ds_write_b16_d16_hi v134, v21 offset:35248
	ds_write_b16 v133, v22 offset:35392
	ds_write_b16_d16_hi v134, v22 offset:35536
	ds_write_b16 v133, v23 offset:35680
	ds_write_b16_d16_hi v134, v23 offset:35824
	ds_write_b128 v135, v[28:31]
	ds_write_b128 v181, v[32:35] offset:53248
	ds_write_b128 v135, v[36:39] offset:17408
	ds_write_b128 v182, v[40:43] offset:53248
	s_and_saveexec_b64 s[0:1], s[16:17]
	ds_write_b32 v119, v75
	s_or_b64 exec, exec, s[0:1]
	s_add_i32 s86, s87, 1
	s_and_b32 s101, s86, 7
	s_cmp_eq_u32 s101, 0
	s_cselect_b32 s101, 0x7f8, 0
	s_add_i32 s86, s86, s101
	s_cmpk_gt_i32 s86, 0xfff
	s_cselect_b64 s[64:65], -1, 0
	s_waitcnt vmcnt(4)
	v_mov_b64_e32 v[46:47], v[26:27]
	s_and_b64 vcc, exec, s[64:65]
	v_mov_b64_e32 v[102:103], v[100:101]
	v_mov_b64_e32 v[104:105], v[98:99]
	v_mov_b64_e32 v[106:107], v[90:91]
	v_mov_b64_e32 v[108:109], v[86:87]
	v_mov_b64_e32 v[44:45], v[24:25]
	s_waitcnt lgkmcnt(0)
	s_barrier
	s_cbranch_vccnz .LBB0_579
	s_and_b32 s43, s86, 0xff
	s_lshl_b32 s0, s86, 3
	s_and_b32 s0, s0, 0xffffc000
	s_lshl_b32 s1, s43, 6
	s_or_b32 s89, s0, s1
	s_bfe_u32 s88, s86, 0x30008
	v_or_b32_e32 v0, s89, v129
	v_mov_b64_e32 v[44:45], s[52:53]
	v_mad_i64_i32 v[0:1], s[0:1], v0, s71, v[44:45]
	s_lshl_b32 s54, s88, 8
	v_mov_b32_e32 v77, v89
	v_lshl_add_u64 v[0:1], v[0:1], 0, s[54:55]
	v_add_u32_e32 v10, s89, v111
	v_lshl_add_u64 v[0:1], v[0:1], 0, v[76:77]
	v_mad_i64_i32 v[10:11], s[0:1], v10, s71, v[44:45]
	s_cmp_lg_u32 s43, 0
	v_add_co_u32_e32 v2, vcc, s72, v0
	s_cselect_b64 s[0:1], -1, 0
	s_nop 0
	v_addc_co_u32_e32 v3, vcc, 0, v1, vcc
	s_cmp_lg_u64 s[0:1], 0
	v_add_co_u32_e32 v8, vcc, s73, v0
	v_lshl_add_u64 v[10:11], v[10:11], 0, s[54:55]
	s_subb_u32 s42, s86, 0
	v_addc_co_u32_e32 v9, vcc, 0, v1, vcc
	v_lshl_add_u64 v[16:17], v[10:11], 0, v[76:77]
	s_cmp_eq_u32 s43, 0
	v_add_co_u32_e32 v12, vcc, s72, v16
	s_cselect_b64 s[0:1], -1, 0
	s_ashr_i32 s43, s42, 31
	v_addc_co_u32_e32 v13, vcc, 0, v17, vcc
	s_lshl_b64 s[90:91], s[42:43], 15
	v_add_co_u32_e32 v20, vcc, s73, v16
	v_lshl_add_u64 v[36:37], v[92:93], 0, s[90:91]
	v_mov_b32_e32 v81, v89
	v_mov_b32_e32 v83, v89
	v_addc_co_u32_e32 v21, vcc, 0, v17, vcc
	v_lshl_add_u64 v[38:39], v[36:37], 0, v[80:81]
	v_lshl_add_u64 v[32:33], v[36:37], 0, v[82:83]
	s_lshl_b64 s[90:91], s[42:43], 9
	s_lshl_b64 s[42:43], s[42:43], 2
	global_load_dwordx4 v[0:3], v[2:3], off offset:2048
	s_nop 0
	global_load_dwordx4 v[4:7], v[8:9], off
	s_nop 0
	global_load_dwordx4 v[8:11], v[8:9], off offset:2048
	s_nop 0
	global_load_dwordx4 v[12:15], v[12:13], off offset:2048
	s_nop 0
	global_load_dwordx4 v[16:19], v[20:21], off
	s_nop 0
	global_load_dwordx4 v[20:23], v[20:21], off offset:2048
	s_nop 0
	global_load_dwordx4 v[28:31], v[38:39], off
	s_nop 0
	global_load_dwordx4 v[32:35], v[32:33], off
	v_add_co_u32_e32 v38, vcc, s74, v38
	v_mov_b32_e32 v79, v89
	s_add_u32 s42, s66, s42
	v_addc_co_u32_e32 v39, vcc, 0, v39, vcc
	v_lshl_add_u64 v[40:41], v[36:37], 0, v[78:79]
	s_addc_u32 s43, s67, s43
	v_or_b32_e32 v56, s89, v110
	global_load_dwordx4 v[36:39], v[38:39], off
	s_nop 0
	global_load_dwordx4 v[40:43], v[40:41], off
	v_mov_b32_e32 v73, v89
	global_load_dword v214, v89, s[42:43]
	v_mad_i64_i32 v[50:51], s[42:43], v56, s71, v[44:45]
	v_lshl_add_u64 v[50:51], v[50:51], 0, s[54:55]
	v_or_b32_e32 v49, 16, v56
	v_lshl_add_u64 v[50:51], v[50:51], 0, v[72:73]
	v_mov_b32_e32 v75, v89
	v_mad_i64_i32 v[52:53], s[42:43], v49, s71, v[44:45]
	v_lshl_add_u64 v[50:51], v[50:51], 0, v[74:75]
	v_lshl_add_u64 v[52:53], v[52:53], 0, s[54:55]
	v_or_b32_e32 v49, 32, v56
	v_add_co_u32_e32 v50, vcc, s75, v50
	v_lshl_add_u64 v[52:53], v[52:53], 0, v[72:73]
	v_mad_i64_i32 v[54:55], s[42:43], v49, s71, v[44:45]
	v_addc_co_u32_e32 v51, vcc, 0, v51, vcc
	v_lshl_add_u64 v[52:53], v[52:53], 0, v[74:75]
	v_lshl_add_u64 v[54:55], v[54:55], 0, s[54:55]
	v_add_co_u32_e32 v52, vcc, s75, v52
	v_lshl_add_u64 v[54:55], v[54:55], 0, v[72:73]
	s_nop 0
	v_addc_co_u32_e32 v53, vcc, 0, v53, vcc
	v_lshl_add_u64 v[54:55], v[54:55], 0, v[74:75]
	v_lshl_add_u64 v[46:47], v[96:97], 0, s[90:91]
	v_add_co_u32_e32 v54, vcc, s75, v54
	v_mov_b32_e32 v85, 0
	s_nop 0
	v_addc_co_u32_e32 v55, vcc, 0, v55, vcc
	global_load_dword v215, v[46:47], off
	global_load_dwordx2 v[102:103], v[50:51], off
	global_load_dwordx2 v[104:105], v[52:53], off
	global_load_dwordx2 v[106:107], v[54:55], off
	v_or_b32_e32 v46, 48, v56
	v_mad_i64_i32 v[44:45], s[42:43], v46, s71, v[44:45]
	v_lshl_add_u64 v[44:45], v[44:45], 0, s[54:55]
	v_lshl_add_u64 v[44:45], v[44:45], 0, v[72:73]
	v_lshl_add_u64 v[44:45], v[44:45], 0, v[74:75]
	v_add_co_u32_e32 v44, vcc, 0x3000, v44
	s_lshl_b32 s54, s88, 9
	s_nop 0
	v_addc_co_u32_e32 v45, vcc, 0, v45, vcc
	global_load_dwordx2 v[108:109], v[44:45], off
	v_lshl_add_u64 v[44:45], v[94:95], 0, s[54:55]
	global_load_dwordx4 v[44:47], v[44:45], off
	v_mov_b32_e32 v73, 0
	s_and_saveexec_b64 s[42:43], s[2:3]
	s_cbranch_execz .LBB0_578
	v_or_b32_e32 v50, s89, v128
	v_ashrrev_i32_e32 v51, 31, v50
	v_lshlrev_b64 v[50:51], 6, v[50:51]
	v_lshl_add_u64 v[50:51], s[50:51], 0, v[50:51]
	s_lshl_b32 s54, s88, 2
	v_lshl_add_u64 v[50:51], v[50:51], 0, s[54:55]
	global_load_dword v85, v[50:51], off
	global_load_dword v73, v[50:51], off offset:32

.LBB0_938:
	s_waitcnt vmcnt(19)
	v_lshlrev_b64 v[0:1], 13, v[176:177]
	s_waitcnt vmcnt(9)
	v_lshl_add_u64 v[40:41], v[172:173], 0, v[0:1]
	global_load_dwordx4 v[0:3], v[152:153], off
	global_load_dwordx4 v[4:7], v[152:153], off offset:1024
	global_load_dwordx4 v[8:11], v[154:155], off
	global_load_dwordx4 v[12:15], v[154:155], off offset:1024
	global_load_dwordx4 v[64:67], v[40:41], off nt
	global_load_dwordx4 v[68:71], v[40:41], off offset:1024 nt
	global_load_dwordx4 v[16:19], v[152:153], off offset:2048
	global_load_dwordx4 v[20:23], v[152:153], off offset:3072
	global_load_dwordx4 v[24:27], v[154:155], off offset:2048
	global_load_dwordx4 v[28:31], v[154:155], off offset:3072
	global_load_dwordx4 v[76:79], v[40:41], off offset:2048 nt
	global_load_dwordx4 v[80:83], v[40:41], off offset:3072 nt
	global_load_dwordx4 v[32:35], v[156:157], off
	global_load_dwordx4 v[36:39], v[158:159], off
	v_add_co_u32_e32 v72, vcc, s41, v40
	s_mov_b32 s0, 0
	s_nop 0
	v_addc_co_u32_e32 v73, vcc, 0, v41, vcc
	global_load_dwordx4 v[40:43], v[160:161], off
	global_load_dwordx4 v[44:47], v[162:163], off
	global_load_dwordx4 v[104:107], v[72:73], off nt
	global_load_dwordx4 v[112:115], v[72:73], off offset:1024 nt
	global_load_dwordx4 v[48:51], v[164:165], off
	global_load_dwordx4 v[52:55], v[166:167], off
	global_load_dwordx4 v[56:59], v[168:169], off
	global_load_dwordx4 v[60:63], v[170:171], off
	global_load_dwordx4 v[120:123], v[72:73], off offset:2048 nt
	global_load_dwordx4 v[124:127], v[72:73], off offset:3072 nt
	s_waitcnt vmcnt(0)
	s_branch .LBB0_940

.LBB0_940:
	v_add_u32_e32 v72, s0, v207
	v_ashrrev_i32_e32 v73, 31, v72
	v_lshlrev_b64 v[72:73], 13, v[72:73]
	v_lshl_add_u64 v[128:129], s[78:79], 0, v[72:73]
	s_cmp_eq_u32 s0, 15
	v_lshlrev_b32_e32 v138, 2, v136
	v_mov_b64_e32 v[88:89], v[64:65]
	v_mov_b64_e32 v[90:91], v[66:67]
	v_mov_b64_e32 v[72:73], v[68:69]
	v_mov_b64_e32 v[74:75], v[70:71]
	v_mov_b64_e32 v[84:85], v[76:77]
	v_mov_b64_e32 v[86:87], v[78:79]
	v_mov_b64_e32 v[92:93], v[80:81]
	v_mov_b64_e32 v[94:95], v[82:83]
	v_mov_b64_e32 v[96:97], v[104:105]
	v_mov_b64_e32 v[98:99], v[106:107]
	v_mov_b64_e32 v[100:101], v[112:113]
	v_mov_b64_e32 v[102:103], v[114:115]
	v_mov_b64_e32 v[108:109], v[120:121]
	v_mov_b64_e32 v[110:111], v[122:123]
	v_mov_b64_e32 v[116:117], v[124:125]
	v_mov_b64_e32 v[118:119], v[126:127]
	s_cbranch_scc1 .LBB0_939
	v_lshl_add_u64 v[96:97], v[128:129], 0, v[138:139]
	v_add_co_u32_e32 v88, vcc, 0x2000, v96
	v_lshl_add_u64 v[92:93], v[96:97], 0, s[76:77]
	s_nop 0
	v_addc_co_u32_e32 v89, vcc, 0, v97, vcc
	v_add_co_u32_e32 v116, vcc, s55, v96
	global_load_dwordx4 v[72:75], v[92:93], off offset:1024 nt
	global_load_dwordx4 v[84:87], v[92:93], off offset:2048 nt
	s_nop 0
	global_load_dwordx4 v[88:91], v[88:89], off nt
	s_nop 0
	global_load_dwordx4 v[92:95], v[92:93], off offset:3072 nt
	v_addc_co_u32_e32 v117, vcc, 0, v97, vcc
	global_load_dwordx4 v[96:99], v[116:117], off nt
	global_load_dwordx4 v[100:103], v[116:117], off offset:1024 nt
	global_load_dwordx4 v[108:111], v[116:117], off offset:2048 nt
	s_nop 0
	global_load_dwordx4 v[116:119], v[116:117], off offset:3072 nt
	s_branch .LBB0_939
